# attention items: relative-position bias looked up from an LDS copy of rel_bias with the per-thread bucket kept in a register (no global loads per item)
# speedup vs baseline: 1.0193x; 1.0054x over previous
; #define LAS __attribute__((address_space(3)))
; __device__ __forceinline__ unsigned xb_ld(unsigned* p) { return __hip_atomic_load(p, __ATOMIC_RELAXED, __HIP_MEMORY_SCOPE_AGENT); }
; __device__ __forceinline__ unsigned xb_xcc_id() { return (unsigned)__builtin_amdgcn_s_getreg((3 << 11) | 20) & 0xFu; }
; __device__ __forceinline__ void xcd_barrier_complete(unsigned* bar, unsigned x, unsigned& nloc, unsigned& nx) {
;   const unsigned G = gridDim.x * gridDim.y * gridDim.z;
;   unsigned sum, cnt, mine, sp = 0u;
;   for (;;) {
;     sum = 0u; cnt = 0u; mine = 0u;
; #pragma unroll
;     for (unsigned j = 0; j < 16; ++j) { const unsigned c = xb_ld(&bar[XB_XCNT(j)]); sum += c; cnt += (c > 0u) ? 1u : 0u; mine = (j == x) ? c : mine; }
;     if (sum == G) break;
;     __builtin_amdgcn_s_sleep(1);
;     if ((++sp & 255u) == 0u) { if (xb_ld(&bar[XB_TMO])) break; if (sp > XB_SPIN_CAP) { atomicAdd(&bar[XB_TMO], 1u); break; } }
;   }
;   nloc = mine > 0u ? mine : 1u; nx = cnt > 0u ? cnt : 1u;
; }
; __device__ __forceinline__ void xcd_barrier(const Params& P, volatile LAS unsigned* st, const int wvi) {
;   XcdBarrier b; b.bar = (unsigned*)(wsp_plain(P) + OFF_CTL + 65536); b.x = xb_xcc_id(); b.st = st;
; __device__ __forceinline__ void attn_item(const Params& P, const int pass, const int item, const int wvi) {
;     ...
;   if (tid < 257) fb[tid] = lptr(P.rel_bias)[(int)P.bucket[tid] * 16 + h];
.LBB0_116:
	s_or_b64 exec, exec, s[0:1]
	s_waitcnt lgkmcnt(0)
	s_add_u32 s52, s50, 0x22700000
	s_addc_u32 s53, s51, 0
	s_lshl_b32 s1, s41, 3
	s_lshl_b32 s31, s42, 3
	v_writelane_b32 v246, s1, 6
	s_add_u32 s1, s50, 0x3df10000
	s_mul_i32 s0, s43, s42
	v_writelane_b32 v246, s1, 7
	s_addc_u32 s1, s51, 0
	v_writelane_b32 v246, s1, 8
	s_mul_i32 s0, s0, s38
	v_writelane_b32 v246, s0, 9
	s_add_u32 s0, s50, 0x3df10200
	s_addc_u32 s1, s51, 0
	v_writelane_b32 v246, s0, 10
	v_mbcnt_lo_u32_b32 v0, -1, 0
	v_mbcnt_hi_u32_b32 v0, -1, v0
	v_add_u32_e32 v0, s48, v0
	v_readlane_b32 s2, v246, 0
	v_readlane_b32 s3, v246, 1
	s_nop 4
	s_load_dwordx2 s[4:5], s[2:3], 0x58
	v_min_u32_e32 v1, 0x100, v0
	global_load_ubyte v255, v1, s[2:3] offset:168
	v_lshlrev_b32_e32 v2, 2, v0
	s_waitcnt lgkmcnt(0)
	global_load_dword v4, v2, s[4:5]
	v_add_u32_e32 v2, 0x23820, v2
	s_waitcnt vmcnt(0)
	ds_write_b32 v2, v4
	s_waitcnt lgkmcnt(0)
	s_barrier
	s_nop 0
	v_writelane_b32 v246, s1, 11
	s_add_u32 s0, s50, 0x3df10400
	s_addc_u32 s1, s51, 0
	v_writelane_b32 v246, s0, 12
	v_mov_b32_e32 v145, 0
	s_nop 0
	v_writelane_b32 v246, s1, 13
	s_add_u32 s0, s50, 0x3df10500
	s_addc_u32 s1, s51, 0
	v_writelane_b32 v246, s0, 14
	v_mov_b32_e32 v165, 0x358637bd
	v_mov_b32_e32 v167, 0x1000
	v_writelane_b32 v246, s1, 15
	s_add_u32 s0, s50, 0x3df10600
	s_addc_u32 s1, s51, 0
	v_writelane_b32 v246, s0, 16
	v_mov_b32_e32 v196, 0x2000
	v_mov_b32_e32 v197, 1
	v_writelane_b32 v246, s1, 17
	s_add_u32 s0, s50, 0x3df10700
	s_addc_u32 s1, s51, 0
	v_writelane_b32 v246, s0, 18
	v_mov_b32_e32 v198, 0x3ecc95a3
	v_bfrev_b32_e32 v199, 0.5
	v_writelane_b32 v246, s1, 19
	s_add_u32 s0, s50, 0x3df10800
	s_addc_u32 s1, s51, 0
	v_writelane_b32 v246, s0, 20
	v_mov_b32_e32 v200, 0x7f800000
	v_mov_b32_e32 v201, 0x7fc00000
	v_writelane_b32 v246, s1, 21
	s_add_u32 s0, s50, 0x3df10900
	s_addc_u32 s1, s51, 0
	v_writelane_b32 v246, s0, 22
	v_mov_b32_e32 v202, 0xff800000
	v_mov_b32_e32 v203, 0x3e800000
	v_writelane_b32 v246, s1, 23
	s_add_u32 s0, s50, 0x3df10a00
	s_addc_u32 s1, s51, 0
	v_writelane_b32 v246, s0, 24
	v_mov_b32_e32 v204, 0x3e000000
	v_mov_b32_e32 v205, 0x35700000
	v_writelane_b32 v246, s1, 25
	s_add_u32 s0, s50, 0x3df10b00
	s_addc_u32 s1, s51, 0
	v_writelane_b32 v246, s0, 26
	v_mov_b32_e32 v206, 0x34f00000
	v_mov_b32_e32 v207, 0x3300
	v_writelane_b32 v246, s1, 27
	s_add_u32 s0, s50, 0x3df10c00
	s_addc_u32 s1, s51, 0
	v_writelane_b32 v246, s0, 28
	v_mov_b32_e32 v208, 0x3000
	v_mov_b32_e32 v209, 0x2c00
	v_writelane_b32 v246, s1, 29
	s_add_u32 s0, s50, 0x3df10d00
	s_addc_u32 s1, s51, 0
	v_writelane_b32 v246, s0, 30
	s_movk_i32 s85, 0x3000
	s_mov_b32 s88, 0x800000
	v_writelane_b32 v246, s1, 31
	s_add_u32 s0, s50, 0x3df10e00
	s_addc_u32 s1, s51, 0
	v_writelane_b32 v246, s0, 32
	s_movk_i32 s89, 0x2000
	s_movk_i32 s90, 0xd000
	v_writelane_b32 v246, s1, 33
	s_add_u32 s0, s50, 0x3df10f00
	s_addc_u32 s1, s51, 0
	v_writelane_b32 v246, s0, 34
	s_movk_i32 s91, 0x1800
	s_mov_b32 s93, 0x32700000
	v_writelane_b32 v246, s1, 35
	s_add_u32 s0, s50, 0x3df11000
	s_addc_u32 s1, s51, 0
	v_writelane_b32 v246, s0, 36
	s_mov_b32 s96, 0x26700000
	s_movk_i32 s97, 0x101
	v_writelane_b32 v246, s1, 37
	s_add_u32 s0, s50, 0x3df11100
	s_addc_u32 s1, s51, 0
	v_writelane_b32 v246, s0, 38
	s_mov_b32 s19, 0
	s_mov_b64 s[86:87], 0x40000
	v_writelane_b32 v246, s1, 39
	s_add_u32 s0, s50, 0x3df11200
	s_addc_u32 s1, s51, 0
	v_writelane_b32 v246, s0, 40
	s_mov_b64 s[46:47], 0x100
	s_nop 0
	v_writelane_b32 v246, s1, 41
	s_add_u32 s0, s50, 0x3df11300
	s_addc_u32 s1, s51, 0
	v_writelane_b32 v246, s0, 42
	s_nop 1
	v_writelane_b32 v246, s1, 43
	s_add_u32 s0, s50, 0x3df13400
	s_addc_u32 s1, s51, 0
	v_writelane_b32 v246, s0, 44
	s_nop 1
	v_writelane_b32 v246, s1, 45
	s_add_u32 s0, s50, 0x3df13500
	s_addc_u32 s1, s51, 0
	v_writelane_b32 v246, s0, 46
	s_lshr_b32 s5, s33, 8
	s_nop 0
	v_writelane_b32 v246, s1, 47
	s_lshl_b32 s0, s39, 10
	v_writelane_b32 v246, s0, 48
	s_and_b32 s0, s33, 0xffffff00
	s_cmpk_eq_i32 s0, 0x100
	s_cselect_b64 s[0:1], -1, 0
	s_lshl_b32 s8, s39, 4
	v_writelane_b32 v246, s0, 49
	s_and_b32 s3, s8, 0x3fffffc0
	s_or_b32 s2, s3, 16
	v_writelane_b32 v246, s1, 50
	v_writelane_b32 v246, s2, 51
	s_lshl_b32 s1, s3, 7
	v_writelane_b32 v246, s3, 52
	s_or_b32 s3, s3, 32
	s_lshl_b32 s0, s39, 12
	v_writelane_b32 v246, s3, 53
	s_or_b32 s4, s8, 48
	s_lshl_b32 s6, s39, 5
	s_and_b32 s0, s0, 0x3000
	s_lshl_b32 s2, s2, 7
	s_lshl_b32 s3, s3, 7
	v_writelane_b32 v246, s4, 54
	s_lshl_b32 s4, s4, 7
	s_lshl_b32 s49, s5, 6
	s_and_b32 s54, s6, 0x60
	s_cmp_eq_u32 s5, 1
	s_cselect_b64 s[56:57], -1, 0
	s_add_u32 s34, s50, 0xa700000
	s_addc_u32 s35, s51, 0
	v_writelane_b32 v246, s6, 55
	s_add_u32 s6, s50, 0x16700000
	s_addc_u32 s7, s51, 0
	v_writelane_b32 v246, s6, 56
	s_lshl_b32 s18, s42, 9
	v_writelane_b32 v243, s56, 0
	v_writelane_b32 v246, s7, 57
	s_add_u32 s6, s50, 0x34700000
	s_addc_u32 s7, s51, 0
	v_writelane_b32 v246, s6, 58
	v_writelane_b32 v243, s57, 1
	v_writelane_b32 v243, s34, 2
	v_writelane_b32 v246, s7, 59
	s_add_u32 s6, s50, 0x34f00000
	s_addc_u32 s7, s51, 0
	v_writelane_b32 v246, s6, 60
	v_writelane_b32 v243, s35, 3
	v_writelane_b32 v243, s18, 4
	v_writelane_b32 v246, s7, 61
	s_add_u32 s6, s50, 0x35700000
	s_addc_u32 s7, s51, 0
	v_writelane_b32 v246, s6, 62
	s_nop 1
	v_writelane_b32 v246, s7, 63
	s_add_u32 s6, s50, 0x3e000000
	s_addc_u32 s7, s51, 0
	v_writelane_b32 v245, s6, 0
	s_nop 1
	v_writelane_b32 v245, s7, 1
	s_add_u32 s6, s50, 0x3e800000
	s_addc_u32 s7, s51, 0
	v_writelane_b32 v245, s6, 2
	s_nop 1
	v_writelane_b32 v245, s7, 3
	s_add_u32 s6, s50, 0x12700000
	s_addc_u32 s7, s51, 0
	v_writelane_b32 v245, s6, 4
	s_add_u32 s5, s50, 0x3df00000
	s_nop 0
	v_writelane_b32 v245, s7, 5
	v_writelane_b32 v245, s5, 6
	s_addc_u32 s5, s51, 0
	s_cmpk_gt_u32 s33, 0xff
	v_writelane_b32 v245, s5, 7
	s_cselect_b64 s[6:7], -1, 0
	s_sub_i32 s5, 11, s39
	s_cmpk_lt_u32 s33, 0x100
	v_writelane_b32 v245, s6, 8
	s_cselect_b64 s[58:59], -1, 0
	s_nop 0
	v_writelane_b32 v245, s7, 9
	s_and_b64 s[6:7], s[58:59], exec
	s_cselect_b32 s5, s39, s5
	s_lshl_b32 s55, s5, 4
	s_ashr_i32 s6, s5, 1
	s_ashr_i32 s60, s55, 31
	s_cmp_gt_u32 s5, 1
	s_cselect_b64 s[10:11], -1, 0
	v_writelane_b32 v245, s10, 10
	s_cmp_lg_u32 s6, 1
	v_writelane_b32 v243, s58, 5
	v_writelane_b32 v245, s11, 11
	s_cselect_b64 s[10:11], -1, 0
	v_writelane_b32 v245, s10, 12
	s_cmp_lg_u32 s6, 2
	v_writelane_b32 v243, s59, 6
	v_writelane_b32 v245, s11, 13
	s_cselect_b64 s[10:11], -1, 0
	v_writelane_b32 v245, s10, 14
	s_cmp_lg_u32 s6, 3
	s_nop 0
	v_writelane_b32 v245, s11, 15
	v_writelane_b32 v245, s6, 16
	v_readlane_b32 s6, v246, 0
	v_readlane_b32 s7, v246, 1
	s_load_dwordx2 s[94:95], s[6:7], 0xa0
	s_cselect_b64 s[10:11], -1, 0
	v_writelane_b32 v245, s10, 17
	s_load_dwordx8 s[20:27], s[6:7], 0x20
	s_waitcnt lgkmcnt(0)
;   unsigned char* ws = wsp(P);
;   const int tid = tidx(wvi);
;   const u16 *W, *Act;
;   int K, nN;
;   if (MODE == 0) { W = (const u16*)(ws + OFF_WIN); Act = (const u16*)(ws + OFF_XN); K = DM; nN = NIN / 256; }
;   else if (MODE == 1) { W = (const u16*)(ws + OFF_WGATE); Act = (const u16*)(ws + OFF_XN); K = DM; nN = 16; }
;   else if (MODE == 2) { W = (const u16*)(ws + OFF_WSSM); Act = (const u16*)(ws + OFF_RA); K = DI; nN = 8; }
;   else if (MODE == 6) { W = (const u16*)(ws + OFF_WATTN); Act = (const u16*)(ws + OFF_Q); K = DM; nN = 8; }
;   else if (MODE == 3) { W = (const u16*)(ws + OFF_WOUT); Act = (const u16*)(ws + OFF_RB + 128 * MiB); K = DM; nN = 8; }
;   else if (MODE == 4) { W = (const u16*)(ws + OFF_WFFI); Act = (const u16*)(ws + OFF_RB + 64 * MiB); K = DM; nN = 44; }
;   else { W = (const u16*)(ws + OFF_WFFO); Act = (const u16*)(ws + OFF_RA); K = DFF; nN = 8; }
	s_add_u32 s33, s94, 0x22700000
	s_addc_u32 s92, s95, 0
	v_writelane_b32 v245, s11, 18
	s_add_u32 s5, s94, 0x3500000
	v_writelane_b32 v245, s5, 19
	s_addc_u32 s5, s95, 0
	s_add_u32 s62, s94, 0x2e700000
	s_addc_u32 s63, s95, 0
	s_add_u32 s10, s94, 0x32700000
	v_writelane_b32 v245, s5, 20
	s_addc_u32 s11, s95, 0
	v_writelane_b32 v245, s10, 21
	v_writelane_b32 v243, s62, 7
	s_nop 0
	v_writelane_b32 v245, s11, 22
	s_add_u32 s10, s94, 0x33700000
	s_addc_u32 s11, s95, 0
	v_writelane_b32 v245, s10, 23
	v_writelane_b32 v243, s63, 8
	s_nop 0
	v_writelane_b32 v245, s11, 24
	s_add_u32 s10, s94, 0x16700000
	s_addc_u32 s11, s95, 0
	s_add_u32 s64, s94, 0x12700000
	v_writelane_b32 v245, s10, 25
	s_addc_u32 s65, s95, 0
	s_add_u32 s5, s94, 0x3df10000
	v_writelane_b32 v245, s11, 26
	v_writelane_b32 v245, s5, 27
	s_addc_u32 s5, s95, 0
	s_add_u32 s10, s94, 0x3df10200
	v_writelane_b32 v245, s5, 28
	s_addc_u32 s11, s95, 0
	v_writelane_b32 v245, s10, 29
	s_nop 1
	v_writelane_b32 v245, s11, 30
	s_add_u32 s10, s94, 0x3df10400
	s_addc_u32 s11, s95, 0
	v_writelane_b32 v245, s10, 31
	s_nop 1
	v_writelane_b32 v245, s11, 32
	s_add_u32 s10, s94, 0x3df10500
	s_addc_u32 s11, s95, 0
	v_writelane_b32 v245, s10, 33
	s_nop 1
	v_writelane_b32 v245, s11, 34
	s_add_u32 s10, s94, 0x3df10600
	s_addc_u32 s11, s95, 0
	v_writelane_b32 v245, s10, 35
	s_nop 1
	v_writelane_b32 v245, s11, 36
	s_add_u32 s10, s94, 0x3df10700
	s_addc_u32 s11, s95, 0
	v_writelane_b32 v245, s10, 37
	s_nop 1
	v_writelane_b32 v245, s11, 38
	s_add_u32 s10, s94, 0x3df10800
	s_addc_u32 s11, s95, 0
	v_writelane_b32 v245, s10, 39
	s_nop 1
	v_writelane_b32 v245, s11, 40
	s_add_u32 s10, s94, 0x3df10900
	s_addc_u32 s11, s95, 0
	v_writelane_b32 v245, s10, 41
	s_nop 1
	v_writelane_b32 v245, s11, 42
	s_add_u32 s10, s94, 0x3df10a00
	s_addc_u32 s11, s95, 0
	v_writelane_b32 v245, s10, 43
	s_nop 1
	v_writelane_b32 v245, s11, 44
	s_add_u32 s10, s94, 0x3df10b00
	s_addc_u32 s11, s95, 0
	v_writelane_b32 v245, s10, 45
	s_nop 1
	v_writelane_b32 v245, s11, 46
	s_add_u32 s10, s94, 0x3df10c00
	s_addc_u32 s11, s95, 0
	v_writelane_b32 v245, s10, 47
	s_nop 1
	v_writelane_b32 v245, s11, 48
	s_add_u32 s10, s94, 0x3df10d00
	s_addc_u32 s11, s95, 0
	v_writelane_b32 v245, s10, 49
	s_nop 1
	v_writelane_b32 v245, s11, 50
	s_add_u32 s10, s94, 0x3df10e00
	s_addc_u32 s11, s95, 0
	v_writelane_b32 v245, s10, 51
	s_nop 1
	v_writelane_b32 v245, s11, 52
	s_add_u32 s10, s94, 0x3df10f00
	s_addc_u32 s11, s95, 0
	v_writelane_b32 v245, s10, 53
	s_nop 1
	v_writelane_b32 v245, s11, 54
	s_add_u32 s10, s94, 0x3df11000
	s_addc_u32 s11, s95, 0
	v_writelane_b32 v245, s10, 55
	s_nop 1
	v_writelane_b32 v245, s11, 56
	s_add_u32 s10, s94, 0x3df11100
	s_addc_u32 s11, s95, 0
	v_writelane_b32 v245, s10, 57
	s_nop 1
	v_writelane_b32 v245, s11, 58
	s_add_u32 s10, s94, 0x3df11200
	s_addc_u32 s11, s95, 0
	v_writelane_b32 v245, s10, 59
	s_nop 1
	v_writelane_b32 v245, s11, 60
	s_add_u32 s10, s94, 0x3df11300
	s_addc_u32 s11, s95, 0
	v_writelane_b32 v245, s10, 61
	s_nop 1
	v_writelane_b32 v245, s11, 62
	s_add_u32 s10, s94, 0x3df13400
	s_addc_u32 s11, s95, 0
	v_writelane_b32 v245, s10, 63
	s_nop 1
	v_writelane_b32 v244, s11, 0
	s_add_u32 s10, s94, 0x3df13500
	s_addc_u32 s11, s95, 0
	s_add_u32 s66, s94, 0xa700000
	v_writelane_b32 v244, s10, 1
	s_addc_u32 s67, s95, 0
	v_writelane_b32 v243, s66, 9
	v_writelane_b32 v244, s11, 2
	s_add_u32 s10, s94, 0x35f00000
	s_addc_u32 s11, s95, 0
	v_writelane_b32 v244, s10, 3
	v_writelane_b32 v243, s67, 10
	s_nop 0
	v_writelane_b32 v244, s11, 4
	s_add_u32 s10, s94, 0x26700000
	s_addc_u32 s11, s95, 0
	v_writelane_b32 v244, s10, 5
	s_lshl_b32 s5, s41, 5
	s_nop 0
	v_writelane_b32 v244, s11, 6
	v_writelane_b32 v244, s5, 7
	s_lshl_b32 s5, s42, 5
	s_add_u32 s61, s94, 0x4500000
	s_addc_u32 s68, s95, 0
	s_add_u32 s69, s94, 0x5500000
	s_addc_u32 s70, s95, 0
	s_add_u32 s72, s94, 0x1e700000
	s_addc_u32 s73, s95, 0
	s_add_u32 s71, s94, 0x5d00000
	s_addc_u32 s74, s95, 0
	s_add_u32 s76, s94, 0x1a700000
	s_addc_u32 s77, s95, 0
	s_add_u32 s75, s94, 0x6500000
	v_writelane_b32 v244, s5, 8
	s_addc_u32 s78, s95, 0
	s_or_b32 s5, s54, 16
	v_writelane_b32 v244, s5, 9
	s_or_b32 s5, s54, 0x80
	v_writelane_b32 v244, s5, 10
	s_or_b32 s5, s54, 0x90
	s_add_u32 s79, s94, 0x9100000
	v_writelane_b32 v244, s5, 11
	s_addc_u32 s80, s95, 0
	s_add_i32 s1, s1, 32
	v_writelane_b32 v244, s1, 12
	s_add_i32 s1, s2, 32
	s_add_i32 s0, s0, 32
	v_writelane_b32 v244, s1, 13
	s_add_i32 s1, s3, 32
	v_writelane_b32 v244, s1, 14
	s_add_i32 s1, s4, 32
	s_add_i32 s81, s0, 0x10000
	s_add_i32 s82, s0, 0x14000
	s_add_i32 s83, s0, 0x18000
	s_add_i32 s84, s0, 0x1c000
	s_add_u32 s0, s50, 0x80080
	v_writelane_b32 v244, s1, 15
	s_addc_u32 s1, s51, 0
	v_writelane_b32 v244, s0, 16
	s_load_dwordx2 s[2:3], s[6:7], 0x10
	v_writelane_b32 v243, s61, 11
	v_writelane_b32 v244, s1, 17
	v_writelane_b32 v244, s41, 18
	s_lshl_b32 s0, s41, 7
	v_writelane_b32 v244, s0, 19
	s_mov_b32 s0, s42
	v_writelane_b32 v244, s0, 20
	v_writelane_b32 v243, s68, 12
	v_writelane_b32 v243, s69, 13
	v_writelane_b32 v244, s1, 21
	s_lshl_b32 s0, s42, 7
	v_writelane_b32 v244, s0, 22
	s_add_u32 s0, s94, 0x80080
	s_addc_u32 s1, s95, 0
	v_writelane_b32 v244, s0, 23
	v_writelane_b32 v243, s70, 14
	v_writelane_b32 v243, s72, 15
	v_writelane_b32 v244, s1, 24
	s_add_u32 s0, s94, 0x3580080
	v_writelane_b32 v244, s0, 25
	s_addc_u32 s0, s95, 0
	v_writelane_b32 v244, s0, 26
	s_sub_i32 s0, 32, s48
	s_add_i32 s0, s0, 0x23000
	v_writelane_b32 v244, s0, 27
	v_writelane_b32 v244, s8, 28
	s_sub_i32 s0, 0, s8
	v_writelane_b32 v244, s0, 29
	s_add_u32 s0, s94, 0x4600080
	s_addc_u32 s1, s95, 0
	v_writelane_b32 v244, s0, 30
	s_load_dwordx4 s[8:11], s[6:7], 0x90
	v_writelane_b32 v243, s73, 16
	v_writelane_b32 v244, s1, 31
	s_add_u32 s0, s94, 0x5580080
	s_addc_u32 s1, s95, 0
	v_writelane_b32 v244, s0, 32
	v_writelane_b32 v243, s71, 17
	v_writelane_b32 v243, s74, 18
	v_writelane_b32 v244, s1, 33
	s_add_u32 s0, s94, 0x5d80080
	s_addc_u32 s1, s95, 0
	v_writelane_b32 v244, s0, 34
	v_writelane_b32 v243, s76, 19
	s_nop 0
	v_writelane_b32 v244, s1, 35
	s_add_u32 s0, s94, 0x6580080
	s_addc_u32 s1, s95, 0
	v_writelane_b32 v244, s0, 36
	v_writelane_b32 v243, s77, 20
	v_writelane_b32 v243, s75, 21
	v_writelane_b32 v244, s1, 37
	s_add_u32 s0, s94, 0x9260080
	s_addc_u32 s1, s95, 0
	v_writelane_b32 v244, s0, 38
	v_writelane_b32 v243, s78, 22
	v_writelane_b32 v243, s79, 23
	v_writelane_b32 v244, s1, 39
	s_waitcnt lgkmcnt(0)
; __global__ void __launch_bounds__(NTHR) fwd_megakernel(const Params P) {
;     ...
;   if (threadIdx.x == 0) {
;     bool even = (gridDim.x & 7u) == 0u;
;     for (int j = 0; j < 8; ++j)
;       even = even && (__hip_atomic_load((unsigned*)(P.ws + OFF_CTL + 8192) + j, __ATOMIC_RELAXED, __HIP_MEMORY_SCOPE_AGENT) == gridDim.x / 8u);
;     s_vb[0] = even ? (s_vb[1] + 8 * s_vb[2]) : (int)blockIdx.x;
;   }
;   __syncthreads();
;   for (int pass = 0; pass < NPASS; ++pass) {
	v_writelane_b32 v244, s2, 40
	v_writelane_b32 v243, s80, 24
	v_writelane_b32 v243, s81, 25
	v_writelane_b32 v244, s3, 41
	s_load_dwordx2 s[2:3], s[6:7], 0x78
	v_writelane_b32 v243, s82, 26
	v_writelane_b32 v243, s83, 27
	v_writelane_b32 v243, s55, 28
	v_writelane_b32 v243, s60, 29
	s_waitcnt lgkmcnt(0)
	v_writelane_b32 v244, s2, 42
	v_writelane_b32 v243, s64, 30
	s_mov_b32 s0, 0
	v_writelane_b32 v244, s3, 43
	v_writelane_b32 v244, s8, 44
	v_writelane_b32 v243, s65, 31
	v_writelane_b32 v243, s84, 32
	v_writelane_b32 v244, s9, 45
	v_writelane_b32 v244, s10, 46
	v_writelane_b32 v244, s11, 47
	s_load_dwordx4 s[8:11], s[6:7], 0x40
	v_writelane_b32 v243, s20, 33
	s_waitcnt lgkmcnt(0)
	v_writelane_b32 v244, s8, 48
	s_nop 1
	v_writelane_b32 v244, s9, 49
	v_writelane_b32 v244, s10, 50
	v_writelane_b32 v244, s11, 51
	s_load_dwordx4 s[8:11], s[6:7], 0x58
	v_writelane_b32 v243, s21, 34
	v_writelane_b32 v243, s22, 35
	v_writelane_b32 v243, s23, 36
	v_writelane_b32 v243, s24, 37
	s_waitcnt lgkmcnt(0)
	v_writelane_b32 v244, s8, 52
	v_writelane_b32 v243, s25, 38
	v_writelane_b32 v243, s26, 39
	v_writelane_b32 v244, s9, 53
	v_writelane_b32 v244, s10, 54
	v_writelane_b32 v244, s11, 55
	v_writelane_b32 v244, s48, 56
	v_writelane_b32 v244, s50, 57
	v_writelane_b32 v243, s27, 40
	s_nop 0
	v_writelane_b32 v244, s51, 58
	v_writelane_b32 v244, s52, 59
	s_nop 1
	v_writelane_b32 v244, s53, 60
	v_writelane_b32 v244, s31, 61
	v_writelane_b32 v244, s49, 62
	v_writelane_b32 v244, s54, 63
	s_branch .LBB0_118

; __device__ __forceinline__ void attn_item(const Params& P, const int pass, const int item, const int wvi) {
;     ...
;   if (tid < 257) fb[tid] = lptr(P.rel_bias)[(int)P.bucket[tid] * 16 + h];
.LBB0_555:
	v_mbcnt_lo_u32_b32 v100, -1, 0
	v_mbcnt_hi_u32_b32 v100, -1, v100
	s_and_b32 s2, s12, 15
	s_waitcnt vmcnt(5)
	v_add_u32_e32 v40, s48, v100
	v_cmp_gt_i32_e32 vcc, s97, v40
	s_and_saveexec_b64 s[0:1], vcc
	s_cbranch_execz .LBB0_557
	v_ashrrev_i32_e32 v41, 31, v40
	s_lshl_b32 s3, s2, 2
	v_lshl_add_u32 v1, v40, 2, 32
	v_add_u32_e32 v1, 0x23000, v1
	v_readlane_b32 s4, v244, 52
	v_readlane_b32 s5, v244, 53
	v_readlane_b32 s6, v244, 54
	v_readlane_b32 s7, v244, 55
	v_lshl_or_b32 v0, v255, 6, s3
	v_add_u32_e32 v0, 0x23820, v0
	ds_read_b32 v0, v0
	s_waitcnt lgkmcnt(0)
	ds_write_b32 v1, v0

; __global__ void __launch_bounds__(NTHR) fwd_megakernel(const Params P) {
	.amdhsa_kernel _Z14fwd_megakernel6Params
		.amdhsa_group_segment_fixed_size 2080
		.amdhsa_private_segment_fixed_size 0
		.amdhsa_kernarg_size 688
		.amdhsa_user_sgpr_count 2
		.amdhsa_user_sgpr_dispatch_ptr 0
		.amdhsa_user_sgpr_queue_ptr 0
		.amdhsa_user_sgpr_kernarg_segment_ptr 1
		.amdhsa_user_sgpr_dispatch_id 0
		.amdhsa_user_sgpr_kernarg_preload_length 0
		.amdhsa_user_sgpr_kernarg_preload_offset 0
		.amdhsa_user_sgpr_private_segment_size 0
		.amdhsa_uses_dynamic_stack 0
		.amdhsa_enable_private_segment 0
		.amdhsa_system_sgpr_workgroup_id_x 1
		.amdhsa_system_sgpr_workgroup_id_y 0
		.amdhsa_system_sgpr_workgroup_id_z 0
		.amdhsa_system_sgpr_workgroup_info 0
		.amdhsa_system_vgpr_workitem_id 2
		.amdhsa_next_free_vgpr 256
		.amdhsa_next_free_sgpr 102
		.amdhsa_accum_offset 256
		.amdhsa_reserve_vcc 1
		.amdhsa_float_round_mode_32 0
		.amdhsa_float_round_mode_16_64 0
		.amdhsa_float_denorm_mode_32 3
		.amdhsa_float_denorm_mode_16_64 3
		.amdhsa_dx10_clamp 1
		.amdhsa_ieee_mode 1
		.amdhsa_fp16_overflow 0
		.amdhsa_tg_split 0
		.amdhsa_exception_fp_ieee_invalid_op 0
		.amdhsa_exception_fp_denorm_src 0
		.amdhsa_exception_fp_ieee_div_zero 0
		.amdhsa_exception_fp_ieee_overflow 0
		.amdhsa_exception_fp_ieee_underflow 0
		.amdhsa_exception_fp_ieee_inexact 0
		.amdhsa_exception_int_div_zero 0
	.end_amdhsa_kernel

; __global__ void __launch_bounds__(NTHR) fwd_megakernel(const Params P) {
amdhsa.kernels:
  - .agpr_count:     0
    .args:
      - .offset:         0
        .size:           432
        .value_kind:     by_value
      - .offset:         432
        .size:           4
        .value_kind:     hidden_block_count_x
      - .offset:         436
        .size:           4
        .value_kind:     hidden_block_count_y
      - .offset:         440
        .size:           4
        .value_kind:     hidden_block_count_z
      - .offset:         444
        .size:           2
        .value_kind:     hidden_group_size_x
      - .offset:         446
        .size:           2
        .value_kind:     hidden_group_size_y
      - .offset:         448
        .size:           2
        .value_kind:     hidden_group_size_z
      - .offset:         450
        .size:           2
        .value_kind:     hidden_remainder_x
      - .offset:         452
        .size:           2
        .value_kind:     hidden_remainder_y
      - .offset:         454
        .size:           2
        .value_kind:     hidden_remainder_z
      - .offset:         472
        .size:           8
        .value_kind:     hidden_global_offset_x
      - .offset:         480
        .size:           8
        .value_kind:     hidden_global_offset_y
      - .offset:         488
        .size:           8
        .value_kind:     hidden_global_offset_z
      - .offset:         496
        .size:           2
        .value_kind:     hidden_grid_dims
      - .offset:         520
        .size:           8
        .value_kind:     hidden_multigrid_sync_arg
      - .offset:         552
        .size:           4
        .value_kind:     hidden_dynamic_lds_size
    .group_segment_fixed_size: 2080
    .kernarg_segment_align: 8
    .kernarg_segment_size: 688
    .language:       OpenCL C
    .language_version:
      - 2
      - 0
    .max_flat_workgroup_size: 512
    .name:           _Z14fwd_megakernel6Params
    .private_segment_fixed_size: 0
    .sgpr_count:     108
    .sgpr_spill_count: 284
    .symbol:         _Z14fwd_megakernel6Params.kd
    .uniform_work_group_size: 1
    .uses_dynamic_stack: false
    .vgpr_count:     256
    .vgpr_spill_count: 0
    .wavefront_size: 64
